# final + mixer loop next-item prefetch block made non-blocking + P1 gate rows moved off the workgroups that also do the sample rows
# speedup vs baseline: 1.0065x; 1.0065x over previous
.LBB0_157:
	s_or_b64 exec, exec, s[2:3]
	s_getpc_b64 s[98:99]
	v_lshlrev_b32_e32 v246, 7, v202
	v_mov_b32_e32 v247, 0
	v_lshl_add_u64 v[246:247], v[246:247], 0, s[98:99]
	global_load_dword v248, v[246:247], off
	s_add_u32 s52, s78, 0xcc0000
	s_addc_u32 s53, s79, 0
	s_sub_i32 s100, 0xff, s96
	s_cmpk_gt_i32 s100, 0x87
	s_cbranch_scc1 .LBB0_163
	s_load_dwordx16 s[36:51], s[0:1], 0x0
	s_load_dword s18, s[0:1], 0xb0
	v_ashrrev_i32_e32 v145, 31, v144
	v_add_u32_e32 v2, 0xfffffe00, v144
	v_lshlrev_b64 v[0:1], 2, v[144:145]
	s_waitcnt lgkmcnt(0)
	s_mov_b64 s[16:17], s[48:49]
	s_add_u32 s2, s16, 0x2000
	s_addc_u32 s3, s17, 0
	s_movk_i32 s19, 0x1ff
	s_mov_b32 s4, s100
	s_branch .LBB0_160
